# P2 queue: up-projection tiles, then top-k batch by batch, the 16 cumulative-sum jobs last
# baseline (speedup 1.0000x reference)
; __global__ void __launch_bounds__(NTHREADS) mega(Params p) {
;     ...
;       constexpr int NTK = 2 * 2052, NUP = 66 * 14, NJ = NTK + NUP + 16;
;       int pending = 0, par = 0;
;       if (threadIdx.x == 0) pending = (int)atomicAdd(p.ctr + l * 2 + 8 * rep, 1u);
;       for (;;) {
;         const int j = next_job(p.ctr + l * 2 + 8 * rep, lds, pending, NJ, par);
;         if (j >= NJ) break;
;         if (j < 16) {
;           cumsum_job(p, j, lds);
;         } else if (j < 16 + NTK) {
;           const int jj = j - 16;
;           const int b = jj & 1, q = 2051 - (jj >> 1);
;           topk_job(p, b, LEAD + 4 * q, lds);
;         } else {
;           const int u = j - 16 - NTK;
;           upproj_tile(p, u / 14, u % 14, lds);
;         }
.LBB0_618:
	s_cmpk_lt_u32 s87, 0x13b4
	s_cbranch_scc0 .Ltks_a
	s_cmpk_lt_u32 s87, 0x39c
	s_cbranch_scc0 .Ltkm_a
	s_addk_i32 s87, 0x1018
	s_branch .Ltks_a
.Ltkm_a:
	s_cmpk_lt_u32 s87, 0x13a4
	s_cbranch_scc1 .Ltkt_a
	s_sub_i32 s87, s87, 0x13a4
	s_branch .Ltks_a
.Ltkt_a:
	s_sub_i32 s2, s87, 0x39c
	s_cmpk_lt_u32 s2, 0x804
	s_cselect_b32 s3, 0, 1
	s_cbranch_scc1 .Ltkb_a
	s_sub_i32 s2, s2, 0x804

; DI int next_job(unsigned* ctr, char* lds, int& pending, int njobs, int& par) {
;   int* sj = (int*)(lds + LDS_JOB);
;   if (threadIdx.x == 0) sj[par] = pending;
;   __syncthreads();
;   const int j = sj[par];
;   par ^= 1;
;   if (threadIdx.x == 0 && j < njobs) pending = (int)atomicAdd(ctr, 1u);
;   return j;
; __global__ void __launch_bounds__(NTHREADS) mega(Params p) {
;     ...
;         const int j = next_job(p.ctr + l * 2 + 8 * rep, lds, pending, NJ, par);
;         if (j >= NJ) break;
;         if (j < 16) {
;           cumsum_job(p, j, lds);
;         } else if (j < 16 + NTK) {
;           const int jj = j - 16;
;           const int b = jj & 1, q = 2051 - (jj >> 1);
;           topk_job(p, b, LEAD + 4 * q, lds);
;         } else {
;           const int u = j - 16 - NTK;
;           upproj_tile(p, u / 14, u % 14, lds);
;         }
.Lsc_end:
	s_waitcnt vmcnt(0) lgkmcnt(0)
	v_lshrrev_b32_e32 v0, 6, v100
	s_mov_b32 s3, s90
	v_readfirstlane_b32 s2, v0
	s_lshl_b32 s4, s87, 1
	s_and_b32 s4, s4, 0x3ffc
	s_sub_i32 s4, 0x209c, s4
	s_bitcmp1_b32 s87, 0
	s_cselect_b32 s5, 0x2100, 0
	s_add_i32 s4, s4, s5
	v_readlane_b32 s6, v240, 13
	v_readlane_b32 s7, v240, 14
	s_lshl_b32 s5, s4, 9
	s_add_u32 s40, s6, s5
	s_addc_u32 s41, s7, 0
	s_add_u32 s42, s40, 0x200
	s_addc_u32 s43, s41, 0
	s_add_u32 s44, s42, 0x200
	s_addc_u32 s45, s43, 0
	s_add_u32 s46, s44, 0x200
	s_addc_u32 s47, s45, 0
	s_mov_b32 s16, 0x55555555
	s_mov_b32 s17, 0x55555555
	s_mov_b32 s18, 0x33333333
	s_mov_b32 s19, 0x33333333
	s_mov_b32 s20, 0xf0f0f0f
	s_mov_b32 s21, 0xf0f0f0f
	s_mov_b32 s22, 0xff00ff
	s_mov_b32 s23, 0xff00ff
	s_mov_b32 s24, 0xffff
	s_mov_b32 s25, 0xffff
	s_mov_b32 s26, 0xffffffff
	s_mov_b32 s27, 0
	v_mov_b32_e32 v20, 1
	v_and_b32_e32 v0, 3, v101
	v_lshlrev_b32_e32 v0, 12, v0
	v_add_u32_e32 v21, 0x4000, v0
	v_add_u32_e32 v25, 0x14000, v0
	v_mov_b32_e32 v29, 0x4000
	v_add_u32_e32 v22, 0x8000, v0
	v_add_u32_e32 v26, 0x18000, v0
	v_mov_b32_e32 v30, 0x8000
	v_add_u32_e32 v23, 0xc000, v0
	v_add_u32_e32 v27, 0x1c000, v0
	v_mov_b32_e32 v31, 0xc000
	v_add_u32_e32 v24, 0x10000, v0
	v_add_u32_e32 v28, 0x20000, v0
	v_mov_b32_e32 v32, 0x10000
	s_movk_i32 s85, 0x100
	s_mov_b32 s56, 0
	s_mov_b32 s58, 0
	v_cmp_eq_u32_e32 vcc, 0, v100
	s_and_saveexec_b64 s[30:31], vcc
	ds_write_b32 v3, v136 offset:768
	s_mov_b64 exec, s[30:31]
	s_waitcnt lgkmcnt(0)
	v_lshlrev_b32_e32 v75, 2, v100
	v_add_u32_e32 v75, 0x2800, v75
	v_lshlrev_b32_e32 v76, 1, v100
	v_add_u32_e32 v76, 0x800, v76
	s_barrier
	v_mov_b32_e32 v4, 0
	v_mov_b32_e32 v5, 0
	v_mov_b32_e32 v6, 0
	v_mov_b32_e32 v7, 0
	v_lshlrev_b32_e32 v0, 4, v100
	v_add_u32_e32 v0, 0x4000, v0
	v_add_u32_e32 v1, 0x10000, v0
	ds_write_b128 v0, v[4:7]
	ds_write_b128 v0, v[4:7] offset:8192
	ds_write_b128 v0, v[4:7] offset:16384
	ds_write_b128 v0, v[4:7] offset:24576
	ds_write_b128 v0, v[4:7] offset:32768
	ds_write_b128 v0, v[4:7] offset:40960
	ds_write_b128 v0, v[4:7] offset:49152
	ds_write_b128 v0, v[4:7] offset:57344
	v_mov_b32_e32 v2, -1
	v_lshlrev_b32_e32 v0, 2, v100
	ds_write_b32 v0, v2 offset:8192
	s_waitcnt lgkmcnt(0)
	s_barrier
	ds_read_b32 v0, v3 offset:768
	s_waitcnt lgkmcnt(0)
	v_readfirstlane_b32 s63, v0
	s_cmpk_lt_u32 s63, 0x13b4
	s_cbranch_scc0 .Ltks_b
	s_cmpk_lt_u32 s63, 0x39c
	s_cbranch_scc0 .Ltkm_b
	s_addk_i32 s63, 0x1018
	s_branch .Ltks_b
.Ltkm_b:
	s_cmpk_lt_u32 s63, 0x13a4
	s_cbranch_scc1 .Ltkt_b
	s_sub_i32 s63, s63, 0x13a4
	s_branch .Ltks_b
.Ltkt_b:
	s_sub_i32 s4, s63, 0x39c
	s_cmpk_lt_u32 s4, 0x804
	s_cselect_b32 s5, 0, 1
	s_cbranch_scc1 .Ltkb_b
	s_sub_i32 s4, s4, 0x804
